# HGRN chain: prefetched value columns packed one stage-group later (no wait right after issuing the loads); RWKV: store-ack waits dropped, gate loads land under exec mask
# speedup vs baseline: 1.0206x; 1.0206x over previous
; __device__ __forceinline__ void rwkv_chain(LAS unsigned char* lds, int cid, const bf16_t* P0, const float* mu, const float* w0, const float* w2, const float* a0, const float* a2, ...
;     ...
;     const int vt = wid >> 1, tt2 = wid & 1;
;     f32x4 st[2]; st[0] = (f32x4){0.f, 0.f, 0.f, 0.f}; st[1] = st[0];
;     __syncthreads();
;     const bf16_t* Pb = P0 + (size_t)b * SEQ * ABPAD;
;     u32x2 rc[5], rpv[5], rnx[5]; unsigned short gcv = 0, gpv = 0, gnv = 0;
;     const unsigned voff = (unsigned)((((int)threadIdx.x >> 4) * ABPAD + ((int)threadIdx.x & 15) * 4) * 2);
;     ...
;     RW_ISSUE(dir ? 127 * 32 : 0);
;     for (int cc = 0; cc < 128; ++cc) {
;         const int t0 = dir ? (127 - cc) * 32 : cc * 32;
;     ...
;         { RW_IDS if (tid < 64) { float lw[32];
; #pragma unroll
;             for (int s = 0; s < 32; ++s) lw[s] = wS[(dir ? 31 - s : s) * 64 + tid];
; #pragma unroll
;             for (int s = 1; s < 32; ++s) lw[s] += lw[s - 1];
; #pragma unroll
;             for (int s = 0; s < 32; ++s) wS[(dir ? 31 - s : s) * 64 + tid] = lw[s]; } }
.LBB0_486:
	s_lshl_b64 s[40:41], s[12:13], 12
	s_lshl_b64 s[2:3], s[38:39], 1
	s_add_u32 s42, s57, s2
	s_addc_u32 s43, s63, s3
	s_lshl_b32 s1, s1, 2
	v_readlane_b32 s2, v253, 30
	v_readlane_b32 s3, v253, 31
	s_add_u32 s44, s2, s1
	s_addc_u32 s45, s3, 0
	s_and_b64 s[2:3], s[10:11], exec
	s_cselect_b32 s90, 1, -1
	s_lshl_b32 s1, s87, 26
	v_readlane_b32 s2, v253, 21
	v_readlane_b32 s3, v253, 22
	s_add_u32 s1, s2, s1
	s_addc_u32 s2, s3, 0
	s_lshl_b32 s0, s0, 1
	s_add_u32 s91, s1, s0
	s_addc_u32 s92, s2, 0
	s_and_b64 s[0:1], s[10:11], exec
	s_movk_i32 s8, 0x1e00
	s_movk_i32 s9, 0x1d00
	s_movk_i32 s12, 0x1b00
	s_movk_i32 s13, 0x1a00
	s_movk_i32 s14, 0x1900
	s_movk_i32 s15, 0x1800
	s_movk_i32 s16, 0x1700
	s_movk_i32 s17, 0x1600
	s_movk_i32 s46, 0x1500
	s_movk_i32 s47, 0x1400
	s_movk_i32 s48, 0x1300
	s_movk_i32 s49, 0x1200
	s_movk_i32 s5, 0x1100
	s_cselect_b32 s93, 0x1f00, 0
	s_cselect_b32 s94, s8, 0x100
	s_cselect_b32 s95, s9, 0x200
	s_cselect_b32 s96, s62, 0x300
	s_cselect_b32 s97, s12, 0x400
	s_cselect_b32 s22, s13, 0x500
	s_cselect_b32 s23, s14, 0x600
	s_cselect_b32 s18, s15, 0x700
	s_cselect_b32 s19, s16, 0x800
	s_cselect_b32 s2, s17, 0x900
	s_cselect_b32 s3, s46, 0xa00
	s_cselect_b32 s56, s47, 0xb00
	s_cselect_b32 s57, s48, 0xc00
	s_cselect_b32 s0, s49, 0xd00
	s_cselect_b32 s1, s5, 0xe00
	s_lshl_b32 s4, s87, 8
	s_and_b64 s[6:7], s[10:11], exec
	s_cselect_b32 s5, 0xe00, s5
	s_cselect_b32 s60, 0xd00, s49
	s_cselect_b32 s61, 0xc00, s48
	s_cselect_b32 s63, 0xb00, s47
	s_cselect_b32 s64, 0xa00, s46
	s_cselect_b32 s65, 0x900, s17
	s_cselect_b32 s66, 0x800, s16
	s_cselect_b32 s67, 0x700, s15
	s_cselect_b32 s68, 0x600, s14
	s_cselect_b32 s69, 0x500, s13
	s_cselect_b32 s70, 0x400, s12
	s_cselect_b32 s71, 0x300, s62
	s_cselect_b32 s72, 0x200, s9
	s_cselect_b32 s73, 0x100, s8
	s_cselect_b32 s8, 0, 0x1f00
	s_sub_i32 s9, 0, s4
	s_mov_b64 s[46:47], 0
	s_movk_i32 s6, 0xfc0
	v_mov_b32_e32 v1, v0
	v_mov_b32_e32 v2, v0
	v_mov_b32_e32 v3, v0
	v_mov_b32_e32 v4, v0
	v_mov_b32_e32 v5, v0
	v_mov_b32_e32 v6, v0
	v_mov_b32_e32 v7, v0
	s_waitcnt vmcnt(0)
	s_branch .LBB0_489

; #define LAS __attribute__((address_space(3)))
; __device__ __forceinline__ unsigned pk2(float lo, float hi) { const f32x2 v = {lo, hi}; return __builtin_bit_cast(unsigned, __builtin_convertvector(v, bf16x2_t)); }
; __device__ __forceinline__ unsigned f2bf(float f) { return pk2(f, 0.f) & 0xffffu; }
; __device__ __forceinline__ float frcp(float x) { return __builtin_amdgcn_rcpf(x); }
; __device__ __forceinline__ float sigmoidf_(float x) { return frcp(1.0f + __expf(-x)); }
; __device__ __forceinline__ void rwkv_chain(LAS unsigned char* lds, int cid, const bf16_t* P0, const float* mu, const float* w0, const float* w2, const float* a0, const float* a2, ...
;     ...
;         { const int tok = tid >> 4, c4 = (tid & 15) * 4;
; #pragma unroll
;         for (int i = 0; i < 5; ++i) {
;             const f32x4 mu4 = *(const LAS f32x4*)(cst + (5 + i) * 64 + c4);
;             const f32x4 cv = (f32x4){bflo(rc[i].x), bfhi(rc[i].x), bflo(rc[i].y), bfhi(rc[i].y)};
;             const f32x4 pv = (f32x4){bflo(rpv[i].x), bfhi(rpv[i].x), bflo(rpv[i].y), bfhi(rpv[i].y)}, nv = (f32x4){bflo(rnx[i].x), bfhi(rnx[i].x), bflo(rnx[i].y), bfhi(rnx[i].y)};
;             const f32x4 xv = cv + mu4 * ((pv + nv) * 0.5f - cv);
;             if (i == 0) *(LAS f32x4*)(rS + tok * 64 + c4) = xv;
;             else if (i == 1) *(LAS f32x4*)(kS + tok * 64 + c4) = xv;
;             else if (i == 2) *(LAS f32x4*)(vS + tok * 64 + c4) = xv;
;             else if (i == 3) { float th[4];
; #pragma unroll
;                 for (int e = 0; e < 4; ++e) { const float ex = __expf(2.f * xv[e]); th[e] = 1.f - 2.f * frcp(ex + 1.f); }
;                 u32x2 w; w.x = pk2(th[0], th[1]); w.y = pk2(th[2], th[3]); *(LAS u32x2*)(wdB + tok * 72 + c4) = w; }
;             else { u32x2 w; w.x = pk2(xv[0], xv[1]); w.y = pk2(xv[2], xv[3]); *(LAS u32x2*)(adB + tok * 72 + c4) = w; }
;         } }
;         if (dir == 0) {
;             const int tok = tid >> 4, c = tid & 15, t = t0 + tok;
;             const float cur = bf2f(gcv), prv = bf2f(gpv), nxt = bf2f(gnv);
;             const float x = cur + cst[10 * 64 + c] * (0.5f * (prv + nxt) - cur);
;             SG[((size_t)b * SEQ + t) * 128 + h * 16 + c] = (bf16_t)f2bf(sigmoidf_(x));
.LBB0_489:
	v_mov_b32_e32 v8, v200
	s_waitcnt vmcnt(4)
	v_lshlrev_b32_e32 v16, 16, v57
	v_ashrrev_i32_e32 v9, 4, v8
	v_and_b32_e32 v8, 15, v8
	v_lshl_add_u32 v25, v8, 4, 0
	v_add_u32_e32 v10, 0x17100, v25
	ds_read_b128 v[10:13], v10
	v_and_b32_e32 v17, 0xffff0000, v57
	v_lshlrev_b32_e32 v20, 16, v55
	v_and_b32_e32 v21, 0xffff0000, v55
	v_lshlrev_b32_e32 v14, 16, v56
	v_and_b32_e32 v15, 0xffff0000, v56
	v_lshlrev_b32_e32 v18, 16, v54
	v_and_b32_e32 v19, 0xffff0000, v54
	v_pk_add_f32 v[16:17], v[20:21], v[16:17]
	v_lshlrev_b32_e32 v20, 16, v53
	v_and_b32_e32 v21, 0xffff0000, v53
	v_pk_add_f32 v[14:15], v[18:19], v[14:15]
	v_lshlrev_b32_e32 v18, 16, v52
	v_and_b32_e32 v19, 0xffff0000, v52
	v_xor_b32_e32 v23, 0x80000000, v21
	v_xor_b32_e32 v22, 0x80000000, v20
	v_pk_fma_f32 v[16:17], v[16:17], 0.5, v[22:23] op_sel_hi:[1,0,1]
	v_xor_b32_e32 v23, 0x80000000, v19
	v_xor_b32_e32 v22, 0x80000000, v18
	v_pk_fma_f32 v[14:15], v[14:15], 0.5, v[22:23] op_sel_hi:[1,0,1]
	v_lshl_add_u32 v27, v9, 8, v25
	s_waitcnt lgkmcnt(0)
	v_pk_fma_f32 v[10:11], v[14:15], v[10:11], v[18:19]
	v_pk_fma_f32 v[12:13], v[16:17], v[12:13], v[20:21]
	ds_write_b128 v27, v[10:13]
	v_add_u32_e32 v10, 0x17200, v25
	ds_read_b128 v[10:13], v10
	v_lshlrev_b32_e32 v16, 16, v61
	v_and_b32_e32 v17, 0xffff0000, v61
	v_lshlrev_b32_e32 v20, 16, v63
	v_and_b32_e32 v21, 0xffff0000, v63
	v_lshlrev_b32_e32 v14, 16, v60
	v_and_b32_e32 v15, 0xffff0000, v60
	v_lshlrev_b32_e32 v18, 16, v62
	v_and_b32_e32 v19, 0xffff0000, v62
	v_pk_add_f32 v[16:17], v[20:21], v[16:17]
	v_lshlrev_b32_e32 v20, 16, v59
	v_and_b32_e32 v21, 0xffff0000, v59
	v_pk_add_f32 v[14:15], v[18:19], v[14:15]
	v_lshlrev_b32_e32 v18, 16, v58
	v_and_b32_e32 v19, 0xffff0000, v58
	v_xor_b32_e32 v23, 0x80000000, v21
	v_xor_b32_e32 v22, 0x80000000, v20
	v_pk_fma_f32 v[16:17], v[16:17], 0.5, v[22:23] op_sel_hi:[1,0,1]
	v_xor_b32_e32 v23, 0x80000000, v19
	v_xor_b32_e32 v22, 0x80000000, v18
	v_pk_fma_f32 v[14:15], v[14:15], 0.5, v[22:23] op_sel_hi:[1,0,1]
	s_waitcnt lgkmcnt(0)
	v_pk_fma_f32 v[12:13], v[16:17], v[12:13], v[20:21]
	v_pk_fma_f32 v[10:11], v[14:15], v[10:11], v[18:19]
	ds_write_b128 v27, v[10:13] offset:8192
	v_add_u32_e32 v10, 0x17300, v25
	ds_read_b128 v[10:13], v10
	v_lshlrev_b32_e32 v16, 16, v67
	v_and_b32_e32 v17, 0xffff0000, v67
	v_lshlrev_b32_e32 v20, 16, v69
	v_and_b32_e32 v21, 0xffff0000, v69
	v_lshlrev_b32_e32 v14, 16, v66
	v_and_b32_e32 v15, 0xffff0000, v66
	v_lshlrev_b32_e32 v18, 16, v68
	v_and_b32_e32 v19, 0xffff0000, v68
	v_pk_add_f32 v[16:17], v[20:21], v[16:17]
	v_lshlrev_b32_e32 v20, 16, v65
	v_and_b32_e32 v21, 0xffff0000, v65
	v_pk_add_f32 v[14:15], v[18:19], v[14:15]
	v_lshlrev_b32_e32 v18, 16, v64
	v_and_b32_e32 v19, 0xffff0000, v64
	v_xor_b32_e32 v23, 0x80000000, v21
	v_xor_b32_e32 v22, 0x80000000, v20
	v_pk_fma_f32 v[16:17], v[16:17], 0.5, v[22:23] op_sel_hi:[1,0,1]
	v_xor_b32_e32 v23, 0x80000000, v19
	v_xor_b32_e32 v22, 0x80000000, v18
	v_pk_fma_f32 v[14:15], v[14:15], 0.5, v[22:23] op_sel_hi:[1,0,1]
	s_waitcnt lgkmcnt(0)
	v_pk_fma_f32 v[12:13], v[16:17], v[12:13], v[20:21]
	v_pk_fma_f32 v[10:11], v[14:15], v[10:11], v[18:19]
	ds_write_b128 v27, v[10:13] offset:16384
	v_add_u32_e32 v10, 0x17400, v25
	ds_read_b128 v[10:13], v10
	v_lshlrev_b32_e32 v14, 16, v72
	v_and_b32_e32 v15, 0xffff0000, v72
	v_lshlrev_b32_e32 v18, 16, v74
	v_and_b32_e32 v19, 0xffff0000, v74
	v_pk_add_f32 v[14:15], v[18:19], v[14:15]
	v_lshlrev_b32_e32 v18, 16, v70
	v_and_b32_e32 v19, 0xffff0000, v70
	v_xor_b32_e32 v23, 0x80000000, v19
	v_xor_b32_e32 v22, 0x80000000, v18
	v_pk_fma_f32 v[14:15], v[14:15], 0.5, v[22:23] op_sel_hi:[1,0,1]
	v_lshlrev_b32_e32 v16, 16, v73
	s_waitcnt lgkmcnt(0)
	v_pk_fma_f32 v[10:11], v[14:15], v[10:11], v[18:19]
	v_and_b32_e32 v17, 0xffff0000, v73
	v_lshlrev_b32_e32 v20, 16, v75
	v_and_b32_e32 v21, 0xffff0000, v75
	v_add_f32_e32 v10, v10, v10
	v_pk_add_f32 v[16:17], v[20:21], v[16:17]
	v_lshlrev_b32_e32 v20, 16, v71
	v_and_b32_e32 v21, 0xffff0000, v71
	v_mul_f32_e32 v10, 0x3fb8aa3b, v10
	v_xor_b32_e32 v23, 0x80000000, v21
	v_xor_b32_e32 v22, 0x80000000, v20
	v_exp_f32_e32 v14, v10
	v_add_f32_e32 v10, v11, v11
	v_pk_fma_f32 v[16:17], v[16:17], 0.5, v[22:23] op_sel_hi:[1,0,1]
	v_mul_f32_e32 v10, 0x3fb8aa3b, v10
	v_exp_f32_e32 v15, v10
	v_pk_fma_f32 v[10:11], v[16:17], v[12:13], v[20:21]
	v_add_f32_e32 v12, 1.0, v14
	v_add_f32_e32 v10, v10, v10
	v_add_f32_e32 v11, v11, v11
	v_mul_f32_e32 v10, 0x3fb8aa3b, v10
	v_mul_f32_e32 v11, 0x3fb8aa3b, v11
	v_exp_f32_e32 v10, v10
	v_exp_f32_e32 v11, v11
	v_add_f32_e32 v13, 1.0, v15
	v_rcp_f32_e32 v12, v12
	v_add_f32_e32 v10, 1.0, v10
	v_add_f32_e32 v11, 1.0, v11
	v_rcp_f32_e32 v13, v13
	v_rcp_f32_e32 v10, v10
	v_rcp_f32_e32 v11, v11
	v_lshlrev_b32_e32 v24, 3, v8
	v_mul_lo_u32 v26, v9, s76
	v_pk_fma_f32 v[12:13], v[12:13], 2.0, 1.0 op_sel_hi:[1,0,0] neg_lo:[1,0,0] neg_hi:[1,0,0]
	v_pk_fma_f32 v[10:11], v[10:11], 2.0, 1.0 op_sel_hi:[1,0,0] neg_lo:[1,0,0] neg_hi:[1,0,0]
	v_add3_u32 v14, s74, v24, v26
	v_cvt_pk_bf16_f32 v12, v12, v13
	v_cvt_pk_bf16_f32 v13, v10, v11
	ds_write_b64 v14, v[12:13]
	v_add_u32_e32 v10, 0x17500, v25
	ds_read_b128 v[10:13], v10
	v_lshlrev_b32_e32 v14, 16, v78
	v_and_b32_e32 v15, 0xffff0000, v78
	v_lshlrev_b32_e32 v18, 16, v80
	v_and_b32_e32 v19, 0xffff0000, v80
	v_lshlrev_b32_e32 v16, 16, v79
	v_and_b32_e32 v17, 0xffff0000, v79
	v_lshlrev_b32_e32 v20, 16, v81
	v_and_b32_e32 v21, 0xffff0000, v81
	v_pk_add_f32 v[14:15], v[18:19], v[14:15]
	v_lshlrev_b32_e32 v18, 16, v76
	v_and_b32_e32 v19, 0xffff0000, v76
	v_pk_add_f32 v[16:17], v[20:21], v[16:17]
	v_lshlrev_b32_e32 v20, 16, v77
	v_and_b32_e32 v21, 0xffff0000, v77
	v_xor_b32_e32 v23, 0x80000000, v19
	v_xor_b32_e32 v22, 0x80000000, v18
	v_pk_fma_f32 v[14:15], v[14:15], 0.5, v[22:23] op_sel_hi:[1,0,1]
	v_xor_b32_e32 v23, 0x80000000, v21
	v_xor_b32_e32 v22, 0x80000000, v20
	v_pk_fma_f32 v[16:17], v[16:17], 0.5, v[22:23] op_sel_hi:[1,0,1]
	s_waitcnt lgkmcnt(0)
	v_pk_fma_f32 v[10:11], v[14:15], v[10:11], v[18:19]
	v_pk_fma_f32 v[12:13], v[16:17], v[12:13], v[20:21]
	v_cvt_pk_bf16_f32 v10, v10, v11
	v_cvt_pk_bf16_f32 v11, v12, v13
	v_cndmask_b32_e64 v12, 0, 1, s[36:37]
	v_add3_u32 v24, s75, v24, v26
	v_cmp_ne_u32_e64 s[12:13], 1, v12
	s_andn2_b64 vcc, exec, s[36:37]
	ds_write_b64 v24, v[10:11]
	s_cbranch_vccnz .LBB0_491
	v_lshl_add_u32 v11, v8, 2, s33
	ds_read_b32 v11, v11 offset:2560
	v_lshlrev_b32_e32 v12, 16, v51
	v_lshlrev_b32_e32 v13, 16, v49
	v_lshlrev_b32_e32 v10, 16, v47
	v_add_f32_e32 v12, v12, v13
	v_fma_f32 v12, v12, 0.5, -v10
	s_waitcnt lgkmcnt(0)
	v_fmac_f32_e32 v10, v12, v11
	v_mul_f32_e32 v10, 0xbfb8aa3b, v10
	v_exp_f32_e32 v12, v10
	v_add_u32_e32 v10, s46, v9
	v_ashrrev_i32_e32 v11, 31, v10
	v_lshl_add_u64 v[10:11], s[40:41], 0, v[10:11]
	v_add_f32_e32 v9, 1.0, v12
	v_rcp_f32_e32 v9, v9
	v_lshlrev_b64 v[10:11], 8, v[10:11]
	v_lshl_add_u64 v[10:11], s[42:43], 0, v[10:11]
	v_lshlrev_b32_e32 v8, 1, v8
	v_cvt_pk_bf16_f32 v12, v9, s0
	v_mov_b32_e32 v9, v38
	v_lshl_add_u64 v[8:9], v[10:11], 0, v[8:9]
	global_store_short v[8:9], v12, off

.LBB0_511:
	v_ashrrev_i32_e32 v10, 4, v14
	v_mov_b64_e32 v[8:9], s[16:17]
	v_mad_i64_i32 v[8:9], s[12:13], v10, s62, v[8:9]
	v_and_b32_e32 v10, 15, v14
	v_lshl_add_u64 v[8:9], s[38:39], 1, v[8:9]
	v_lshlrev_b32_e32 v10, 1, v10
	v_mov_b32_e32 v11, v38
	v_lshl_add_u64 v[8:9], v[8:9], 0, v[10:11]
	v_cndmask_b32_e64 v11, -1, 0, s[14:15]
	v_cndmask_b32_e64 v10, v112, 0, s[14:15]
	v_lshl_add_u64 v[10:11], v[8:9], 0, v[10:11]
	v_mov_b32_e32 v51, 0
	v_mov_b32_e32 v49, 0
	s_mov_b64 s[12:13], exec
	s_andn2_b64 exec, s[12:13], s[14:15]
	global_load_ushort v51, v[10:11], off offset:3328
	s_mov_b64 exec, s[12:13]
	v_cndmask_b32_e64 v10, v113, 0, s[48:49]
	v_mov_b32_e32 v11, v38
	v_lshl_add_u64 v[10:11], v[8:9], 0, v[10:11]
	s_andn2_b64 exec, s[12:13], s[48:49]
	global_load_ushort v49, v[10:11], off offset:3328
	s_mov_b64 exec, s[12:13]
	global_load_ushort v47, v[8:9], off offset:3328

; #define LAS __attribute__((address_space(3)))
; __device__ __forceinline__ unsigned pk2(float lo, float hi) { const f32x2 v = {lo, hi}; return __builtin_bit_cast(unsigned, __builtin_convertvector(v, bf16x2_t)); }
; __device__ __forceinline__ f32x4 mfma16(bf16x8 bfrag, bf16x8 afrag, f32x4 acc) { return __builtin_amdgcn_mfma_f32_16x16x32_bf16(bfrag, afrag, acc, 0, 0, 0); }
; __device__ __forceinline__ void hgrn_chain(LAS unsigned char* lds, int cid, bf16_t* P1, const float* hg_lb, bf16_t* Ob, int ldo, int ocbase, int ocdir) {
;     ...
;         { const int mt = w >> 1;
; #pragma unroll
;           for (int n2 = 0; n2 < 2; ++n2) { const int nt = (w & 1) * 2 + n2; f32x4 acc = (f32x4){0.f, 0.f, 0.f, 0.f};
; #pragma unroll
;               for (int ks = 0; ks < 4; ++ks) acc = mfma16(ldsfrag(KE, HLD, nt * 16, ks * 32, fr, fq), ldsfrag(QE, HLD, mt * 16, ks * 32, fr, fq), acc);
;               const int lrow = mt * 16 + fr; float mv[4];
; #pragma unroll
;               for (int i = 0; i < 4; ++i) { const int s = nt * 16 + fq * 4 + i; mv[i] = (s <= lrow) ? acc[i] : 0.f; }
;               u32x2 o; o.x = pk2(mv[0], mv[1]); o.y = pk2(mv[2], mv[3]); *(LAS u32x2*)(AT + lrow * HLS + nt * 16 + fq * 4) = o; } }
;         __syncthreads();
;         { const int mt = w >> 1;
; #pragma unroll
;           for (int n4 = 0; n4 < 4; ++n4) { const int nt = (w & 1) * 4 + n4; f32x4 acc = (f32x4){0.f, 0.f, 0.f, 0.f};
; #pragma unroll
;               for (int ks = 0; ks < 2; ++ks) acc = mfma16(ldsfrag(VT, HLS, nt * 16, ks * 32, fr, fq), ldsfrag(AT, HLS, mt * 16, ks * 32, fr, fq), acc);
; #pragma unroll
;               for (int ks = 0; ks < 4; ++ks) acc = mfma16(ldsfrag(ST, HLD, nt * 16, ks * 32, fr, fq), ldsfrag(QE, HLD, mt * 16, ks * 32, fr, fq), acc);
;               const int i = mt * 16 + fr, tk = t0 + (dir ? 63 - i : i);
;               u32x2 o; o.x = pk2(acc[0], acc[1]); o.y = pk2(acc[2], acc[3]);
;               *(u32x2*)(Ob + ((size_t)b * SEQ + tk) * ldo + ocbase + ocdir * dir + h * 128 + nt * 16 + fq * 4) = o; } }
.LBB0_1715:
	s_waitcnt lgkmcnt(0)
	s_barrier
	ds_read_b128 v[56:59], v163 offset:17408
	ds_read_b128 v[60:63], v163 offset:17472
	ds_read_b128 v[64:67], v164
	ds_read_b128 v[68:71], v164 offset:64
	s_waitcnt lgkmcnt(1)
	v_mfma_f32_16x16x32_bf16 v[56:59], v[56:59], v[64:67], 0
	ds_read_b128 v[72:75], v163 offset:17536
	ds_read_b128 v[76:79], v163 offset:17600
	s_add_i32 s44, s42, -1
	s_add_i32 s45, s43, 1
	s_waitcnt lgkmcnt(2)
	v_mfma_f32_16x16x32_bf16 v[56:59], v[60:63], v[68:71], v[56:59]
	ds_read_b128 v[60:63], v164 offset:128
	ds_read_b128 v[80:83], v164 offset:192
	s_and_b64 s[36:37], s[24:25], exec
	s_cselect_b32 s36, s44, s45
	s_waitcnt lgkmcnt(1)
	v_mfma_f32_16x16x32_bf16 v[56:59], v[72:75], v[60:63], v[56:59]
	s_add_i32 s43, s43, -1
	s_add_i32 s42, s42, 1
	s_cmp_lg_u32 s43, -2
	s_waitcnt lgkmcnt(0)
	v_mfma_f32_16x16x32_bf16 v[56:59], v[76:79], v[80:83], v[56:59]
	s_nop 7
	v_cndmask_b32_e64 v42, v56, 0, s[8:9]
	v_cndmask_b32_e64 v45, 0, v57, s[10:11]
	v_cndmask_b32_e64 v47, v58, 0, s[12:13]
	v_cndmask_b32_e64 v57, v59, 0, s[14:15]
	v_cvt_pk_bf16_f32 v56, v42, v45
	v_cvt_pk_bf16_f32 v57, v47, v57
	ds_write_b64 v165, v[56:57]
	ds_read_b128 v[56:59], v166 offset:17408
	ds_read_b128 v[72:75], v166 offset:17472
	s_waitcnt lgkmcnt(1)
	v_mfma_f32_16x16x32_bf16 v[56:59], v[56:59], v[64:67], 0
	ds_read_b128 v[64:67], v166 offset:17536
	s_waitcnt lgkmcnt(1)
	v_mfma_f32_16x16x32_bf16 v[56:59], v[72:75], v[68:71], v[56:59]
	ds_read_b128 v[68:71], v166 offset:17600
	s_waitcnt lgkmcnt(1)
	v_mfma_f32_16x16x32_bf16 v[56:59], v[64:67], v[60:63], v[56:59]
	s_waitcnt lgkmcnt(0)
	v_mfma_f32_16x16x32_bf16 v[56:59], v[68:71], v[80:83], v[56:59]
	s_nop 7
	v_cndmask_b32_e64 v42, v56, 0, s[16:17]
	v_cndmask_b32_e64 v45, 0, v57, s[18:19]
	v_cndmask_b32_e64 v47, v58, 0, s[20:21]
	v_cndmask_b32_e64 v57, v59, 0, s[22:23]
	v_cvt_pk_bf16_f32 v56, v42, v45
	v_cvt_pk_bf16_f32 v57, v47, v57
	ds_write_b64 v167, v[56:57]
	s_waitcnt lgkmcnt(0)
	s_barrier
	ds_read_b128 v[56:59], v168 offset:53248
	v_add_u32_e32 v42, v141, v138
	ds_read_b128 v[60:63], v42
	ds_read_b128 v[64:67], v168 offset:53312
	ds_read_b128 v[68:71], v42 offset:64
	s_waitcnt lgkmcnt(2)
	v_mfma_f32_16x16x32_bf16 v[56:59], v[56:59], v[60:63], 0
	ds_read_b128 v[72:75], v170 offset:53248
	ds_read_b128 v[76:79], v170 offset:53312
	ds_read_b128 v[80:83], v172 offset:53248
	ds_read_b128 v[84:87], v172 offset:53312
	v_add_u32_e32 v42, 0x1cc00, v139
	s_waitcnt lgkmcnt(4)
	v_mfma_f32_16x16x32_bf16 v[56:59], v[64:67], v[68:71], v[56:59]
	ds_read_b128 v[64:67], v169
	s_waitcnt lgkmcnt(4)
	v_mfma_f32_16x16x32_bf16 v[72:75], v[72:75], v[60:63], 0
	s_waitcnt lgkmcnt(3)
	v_mfma_f32_16x16x32_bf16 v[72:75], v[76:79], v[68:71], v[72:75]
	ds_read_b128 v[76:79], v164
	ds_read_b128 v[88:91], v169 offset:64
	ds_read_b128 v[92:95], v164 offset:64
	s_waitcnt lgkmcnt(2)
	v_mfma_f32_16x16x32_bf16 v[56:59], v[64:67], v[76:79], v[56:59]
	ds_read_b128 v[64:67], v171
	ds_read_b128 v[96:99], v171 offset:64
	s_waitcnt lgkmcnt(1)
	v_mfma_f32_16x16x32_bf16 v[64:67], v[64:67], v[76:79], v[72:75]
	s_nop 2
	ds_read_b128 v[72:75], v169 offset:128
	v_mfma_f32_16x16x32_bf16 v[56:59], v[88:91], v[92:95], v[56:59]
	s_waitcnt lgkmcnt(1)
	v_mfma_f32_16x16x32_bf16 v[64:67], v[96:99], v[92:95], v[64:67]
	ds_read_b128 v[88:91], v164 offset:128
	ds_read_b128 v[96:99], v169 offset:192
	ds_read_b128 v[100:103], v164 offset:192
	s_waitcnt lgkmcnt(2)
	v_mfma_f32_16x16x32_bf16 v[56:59], v[72:75], v[88:91], v[56:59]
	ds_read_b128 v[72:75], v171 offset:128
	ds_read_b128 v[230:233], v171 offset:192
	s_waitcnt lgkmcnt(1)
	v_mfma_f32_16x16x32_bf16 v[64:67], v[72:75], v[88:91], v[64:67]
	ds_read_b128 v[72:75], v173
	v_mfma_f32_16x16x32_bf16 v[80:83], v[80:83], v[60:63], 0
	v_mfma_f32_16x16x32_bf16 v[80:83], v[84:87], v[68:71], v[80:83]
	ds_read_b128 v[84:87], v173 offset:64
	s_waitcnt lgkmcnt(1)
	v_mfma_f32_16x16x32_bf16 v[72:75], v[72:75], v[76:79], v[80:83]
	v_mfma_f32_16x16x32_bf16 v[56:59], v[96:99], v[100:103], v[56:59]
	s_nop 3
	ds_read_b128 v[80:83], v173 offset:128
	ds_read_b128 v[96:99], v173 offset:192
	s_waitcnt lgkmcnt(2)
	v_mfma_f32_16x16x32_bf16 v[72:75], v[84:87], v[92:95], v[72:75]
	ds_read_b128 v[84:87], v174 offset:53248
	s_waitcnt lgkmcnt(2)
	v_mfma_f32_16x16x32_bf16 v[72:75], v[80:83], v[88:91], v[72:75]
	ds_read_b128 v[80:83], v174 offset:53312
	s_waitcnt lgkmcnt(2)
	v_mfma_f32_16x16x32_bf16 v[72:75], v[96:99], v[100:103], v[72:75]
	ds_read_b128 v[96:99], v175
	s_waitcnt lgkmcnt(2)
	v_mfma_f32_16x16x32_bf16 v[60:63], v[84:87], v[60:63], 0
	v_cvt_pk_bf16_f32 v84, v56, v57
	v_cvt_pk_bf16_f32 v85, v58, v59
	ds_read_b128 v[56:59], v175 offset:64
	s_waitcnt lgkmcnt(2)
	v_mfma_f32_16x16x32_bf16 v[60:63], v[80:83], v[68:71], v[60:63]
	ds_read_b128 v[68:71], v175 offset:128
	s_waitcnt lgkmcnt(2)
	v_mfma_f32_16x16x32_bf16 v[60:63], v[96:99], v[76:79], v[60:63]
	ds_read_b128 v[76:79], v175 offset:192
	v_mfma_f32_16x16x32_bf16 v[64:67], v[230:233], v[100:103], v[64:67]
	v_lshl_add_u32 v230, s36, 6, v184
	v_ashrrev_i32_e32 v231, 31, v230
	v_lshl_add_u64 v[230:231], s[34:35], 0, v[230:231]
	s_waitcnt lgkmcnt(2)
	v_mfma_f32_16x16x32_bf16 v[56:59], v[56:59], v[92:95], v[60:63]
	v_mad_u64_u32 v[80:81], s[36:37], v230, s40, v[54:55]
	v_mad_i32_i24 v81, v231, s40, v81
	s_nop 0
	v_cvt_pk_bf16_f32 v60, v64, v65
	v_cvt_pk_bf16_f32 v61, v66, v67
	global_store_dwordx2 v[80:81], v[60:61], off offset:2080
	v_cvt_pk_bf16_f32 v60, v72, v73
	v_cvt_pk_bf16_f32 v61, v74, v75
	global_store_dwordx2 v[80:81], v[60:61], off offset:2112
	ds_read_b128 v[60:63], v42
	s_waitcnt lgkmcnt(2)
	v_mfma_f32_16x16x32_bf16 v[56:59], v[68:71], v[88:91], v[56:59]
	global_store_dwordx2 v[80:81], v[84:85], off offset:2048
	s_waitcnt lgkmcnt(0)
; #define LAS __attribute__((address_space(3)))
; __device__ __forceinline__ unsigned pk2(float lo, float hi) { const f32x2 v = {lo, hi}; return __builtin_bit_cast(unsigned, __builtin_convertvector(v, bf16x2_t)); }
; __device__ __forceinline__ f32x4 mfma16(bf16x8 bfrag, bf16x8 afrag, f32x4 acc) { return __builtin_amdgcn_mfma_f32_16x16x32_bf16(bfrag, afrag, acc, 0, 0, 0); }
; __device__ __forceinline__ void hgrn_chain(LAS unsigned char* lds, int cid, bf16_t* P1, const float* hg_lb, bf16_t* Ob, int ldo, int ocbase, int ocdir) {
;     ...
;         for (int i = 0; i < 16; i += 2) *(LAS unsigned*)(VT + dcol * HLS + i0 + i) = (unsigned)rv[i] | ((unsigned)rv[i + 1] << 16);
;     ...
; #pragma unroll
;         for (int nt = 0; nt < 8; ++nt) { const f32x4 el = *(const LAS f32x4*)(lastS + nt * 16 + fq * 4); st[nt] = st[nt] * el;
; #pragma unroll
;             for (int ks = 0; ks < 2; ++ks) st[nt] = mfma16(ldsfrag(KLT, HLS, nt * 16, ks * 32, fr, fq), ldsfrag(VT, HLS, w * 16, ks * 32, fr, fq), st[nt]); }
;         __syncthreads();
; #pragma unroll
;         for (int nt = 0; nt < 8; ++nt) { u32x2 o; o.x = pk2(st[nt][0], st[nt][1]); o.y = pk2(st[nt][2], st[nt][3]); *(LAS u32x2*)(ST + (w * 16 + fr) * HLD + nt * 16 + fq * 4) = o; }
	v_pk_mul_f32 v[0:1], v[0:1], v[60:61]
	v_mfma_f32_16x16x32_bf16 v[56:59], v[76:79], v[100:103], v[56:59]
	v_mul_f32_e64 v2, v2, v62
	v_mul_f32_e64 v3, v3, v63
	s_nop 5
	v_cvt_pk_bf16_f32 v56, v56, v57
	v_cvt_pk_bf16_f32 v57, v58, v59
	global_store_dwordx2 v[80:81], v[56:57], off offset:2144
	ds_read_b128 v[56:59], v176 offset:34816
	ds_read_b128 v[64:67], v42 offset:64
	ds_read_b128 v[60:63], v176 offset:34880
	ds_read_b128 v[68:71], v177 offset:53248
	ds_read_b128 v[72:75], v177 offset:53312
	s_waitcnt lgkmcnt(1)
	v_mfma_f32_16x16x32_bf16 v[0:3], v[56:59], v[68:71], v[0:3]
	v_mul_f32_e64 v4, v4, v64
	v_mul_f32_e64 v5, v5, v65
	ds_read_b128 v[76:79], v176 offset:37120
	ds_read_b128 v[80:83], v42 offset:128
	v_pk_mul_f32 v[6:7], v[6:7], v[66:67]
	ds_read_b128 v[56:59], v176 offset:37184
	ds_read_b128 v[64:67], v42 offset:192
	s_waitcnt lgkmcnt(4)
	v_mfma_f32_16x16x32_bf16 v[0:3], v[60:63], v[72:75], v[0:3]
	ds_read_b128 v[60:63], v176 offset:39424
	s_waitcnt lgkmcnt(3)
	v_pk_mul_f32 v[8:9], v[8:9], v[80:81]
	v_pk_mul_f32 v[10:11], v[10:11], v[82:83]
	v_mfma_f32_16x16x32_bf16 v[4:7], v[76:79], v[68:71], v[4:7]
	ds_read_b128 v[76:79], v176 offset:39488
	s_waitcnt lgkmcnt(2)
	v_pk_mul_f32 v[16:17], v[16:17], v[64:65]
	v_pk_mul_f32 v[18:19], v[18:19], v[66:67]
	v_mfma_f32_16x16x32_bf16 v[4:7], v[56:59], v[72:75], v[4:7]
	ds_read_b128 v[56:59], v42 offset:256
	ds_read_b128 v[64:67], v176 offset:41728
	ds_read_b128 v[80:83], v176 offset:41792
	s_waitcnt lgkmcnt(2)
	v_pk_mul_f32 v[12:13], v[12:13], v[56:57]
	v_mfma_f32_16x16x32_bf16 v[8:11], v[60:63], v[68:71], v[8:11]
	ds_read_b128 v[60:63], v42 offset:320
	v_pk_mul_f32 v[14:15], v[14:15], v[58:59]
	s_waitcnt lgkmcnt(0)
	v_pk_mul_f32 v[24:25], v[24:25], v[60:61]
	v_mfma_f32_16x16x32_bf16 v[16:19], v[64:67], v[68:71], v[16:19]
	v_mul_f32_e64 v26, v26, v62
	v_mul_f32_e64 v27, v27, v63
	v_mfma_f32_16x16x32_bf16 v[8:11], v[76:79], v[72:75], v[8:11]
	ds_read_b128 v[56:59], v176 offset:44032
	ds_read_b128 v[76:79], v176 offset:44096
	ds_read_b128 v[60:63], v42 offset:384
	ds_read_b128 v[64:67], v176 offset:46336
	ds_read_b128 v[84:87], v176 offset:46400
	s_waitcnt lgkmcnt(2)
	v_pk_mul_f32 v[20:21], v[20:21], v[60:61]
	v_mfma_f32_16x16x32_bf16 v[16:19], v[80:83], v[72:75], v[16:19]
	ds_read_b128 v[80:83], v42 offset:448
	v_pk_mul_f32 v[22:23], v[22:23], v[62:63]
	s_waitcnt lgkmcnt(0)
	v_pk_mul_f32 v[28:29], v[28:29], v[80:81]
	v_mfma_f32_16x16x32_bf16 v[12:15], v[56:59], v[68:71], v[12:15]
	ds_read_b128 v[56:59], v176 offset:48640
	ds_read_b128 v[60:63], v176 offset:48704
	v_pk_mul_f32 v[30:31], v[30:31], v[82:83]
	v_mfma_f32_16x16x32_bf16 v[12:15], v[76:79], v[72:75], v[12:15]
	ds_read_b128 v[76:79], v176 offset:50944
	ds_read_b128 v[80:83], v176 offset:51008
	s_waitcnt lgkmcnt(0)
	s_barrier
	v_mfma_f32_16x16x32_bf16 v[24:27], v[64:67], v[68:71], v[24:27]
	v_cvt_pk_bf16_f32 v64, v0, v1
	v_cvt_pk_bf16_f32 v65, v2, v3
	v_mfma_f32_16x16x32_bf16 v[20:23], v[56:59], v[68:71], v[20:23]
	v_cvt_pk_bf16_f32 v56, v8, v9
	v_cvt_pk_bf16_f32 v57, v10, v11
	v_cvt_pk_bf16_f32 v58, v16, v17
	v_mfma_f32_16x16x32_bf16 v[28:31], v[76:79], v[68:71], v[28:31]
	v_cvt_pk_bf16_f32 v59, v18, v19
	ds_write2_b64 v178, v[56:57], v[58:59] offset0:8 offset1:12
	v_cvt_pk_bf16_f32 v56, v12, v13
	v_mfma_f32_16x16x32_bf16 v[24:27], v[84:87], v[72:75], v[24:27]
	v_cvt_pk_bf16_f32 v57, v14, v15
	v_cvt_pk_bf16_f32 v66, v4, v5
	v_cvt_pk_bf16_f32 v67, v6, v7
	v_mfma_f32_16x16x32_bf16 v[20:23], v[60:63], v[72:75], v[20:23]
	ds_write2_b64 v178, v[64:65], v[66:67] offset1:4
	s_nop 2
	v_cvt_pk_bf16_f32 v58, v24, v25
	v_cvt_pk_bf16_f32 v59, v26, v27
	v_mfma_f32_16x16x32_bf16 v[28:31], v[80:83], v[72:75], v[28:31]
	ds_write2_b64 v178, v[56:57], v[58:59] offset0:16 offset1:20
	v_cvt_pk_bf16_f32 v56, v20, v21
	v_cvt_pk_bf16_f32 v57, v22, v23
	s_nop 4
	v_cvt_pk_bf16_f32 v58, v28, v29
	v_cvt_pk_bf16_f32 v59, v30, v31
	ds_write2_b64 v178, v[56:57], v[58:59] offset0:24 offset1:28
	s_cbranch_scc0 .LBB0_1711
	s_waitcnt vmcnt(6)
	v_lshl_or_b32 v32, v236, 16, v235
	v_lshl_or_b32 v33, v238, 16, v237
	v_lshl_or_b32 v34, v240, 16, v239
	v_lshl_or_b32 v35, v242, 16, v241
	v_lshl_or_b32 v36, v244, 16, v243
	v_lshl_or_b32 v39, v246, 16, v245
	v_lshl_or_b32 v37, v248, 16, v247
	v_lshl_or_b32 v38, v250, 16, v249
; #define LAS __attribute__((address_space(3)))
; __device__ __forceinline__ unsigned pk2(float lo, float hi) { const f32x2 v = {lo, hi}; return __builtin_bit_cast(unsigned, __builtin_convertvector(v, bf16x2_t)); }
; __device__ __forceinline__ unsigned f2bf(float f) { return pk2(f, 0.f) & 0xffffu; }
; __device__ __forceinline__ float frcp(float x) { return __builtin_amdgcn_rcpf(x); }
; __device__ __forceinline__ float sigmoidf_(float x) { return frcp(1.0f + __expf(-x)); }
; __device__ __forceinline__ void hgrn_chain(LAS unsigned char* lds, int cid, bf16_t* P1, const float* hg_lb, bf16_t* Ob, int ldo, int ocbase, int ocdir) {
;     ...
;         float gq[16], gk[16], gc[16]; float run = 1.0f;
; #pragma unroll
;         for (int i = 0; i < 16; ++i) { const float q = bf2f(rq[i]), fr_ = bf2f(rf[i]);
;             const float f = lbv + (1.0f - lbv) * sigmoidf_(fr_); run *= f; gq[i] = q; gk[i] = 1.0f - f; gc[i] = run; }
;         totS[qtr * 128 + dcol] = run;
; #pragma unroll
;         for (int i = 0; i < 16; i += 2) *(LAS unsigned*)(VT + dcol * HLS + i0 + i) = (unsigned)rv[i] | ((unsigned)rv[i + 1] << 16);
;         __syncthreads();
;         { float pre = 1.0f, tot = 1.0f;
; #pragma unroll
;           for (int q4 = 0; q4 < 4; ++q4) { const float tq = totS[q4 * 128 + dcol]; if (q4 < qtr) pre *= tq; tot *= tq; }
;           const float etot = tot;
;           if (qtr == 0) lastS[dcol] = etot;
; #pragma unroll
;           for (int i = 0; i < 16; i += 2) { const float e0 = fmaxf(pre * gc[i], 1e-30f), e1 = fmaxf(pre * gc[i + 1], 1e-30f), n0 = frcp(e0), n1 = frcp(e1), l0 = etot * n0, l1 = etot * n1;
;               QE[(i0 + i) * HLD + dcol] = (bf16_t)f2bf(gq[i] * e0); QE[(i0 + i + 1) * HLD + dcol] = (bf16_t)f2bf(gq[i + 1] * e1);
;               KE[(i0 + i) * HLD + dcol] = (bf16_t)f2bf(gk[i] * n0); KE[(i0 + i + 1) * HLD + dcol] = (bf16_t)f2bf(gk[i + 1] * n1);
;               *(LAS unsigned*)(KLT + dcol * HLS + i0 + i) = pk2(gk[i] * l0, gk[i + 1] * l1); } }
.LBB0_1716:
	s_waitcnt vmcnt(20)
	v_lshlrev_b32_e32 v42, 16, v180
	v_mul_f32_e32 v42, 0xbfb8aa3b, v42
	s_waitcnt vmcnt(18)
	v_lshlrev_b32_e32 v45, 16, v182
	v_exp_f32_e32 v42, v42
	v_mul_f32_e32 v45, 0xbfb8aa3b, v45
	v_exp_f32_e32 v45, v45
	s_waitcnt vmcnt(14)
	v_lshlrev_b32_e32 v47, 16, v204
	v_add_f32_e32 v42, 1.0, v42
	v_rcp_f32_e32 v56, v42
	v_add_f32_e32 v42, 1.0, v45
	v_lshlrev_b32_e32 v45, 16, v185
	v_mul_f32_e32 v45, 0xbfb8aa3b, v45
	v_exp_f32_e32 v45, v45
	v_mul_f32_e32 v47, 0xbfb8aa3b, v47
	v_exp_f32_e32 v47, v47
	v_rcp_f32_e32 v57, v42
	v_add_f32_e32 v42, 1.0, v45
	v_rcp_f32_e32 v58, v42
	v_add_f32_e32 v42, 1.0, v47
	v_rcp_f32_e32 v59, v42
	s_waitcnt vmcnt(12)
	v_lshlrev_b32_e32 v42, 16, v206
	v_mul_f32_e32 v42, 0xbfb8aa3b, v42
	v_lshlrev_b32_e32 v45, 16, v207
	v_exp_f32_e32 v42, v42
	v_mul_f32_e32 v45, 0xbfb8aa3b, v45
	v_exp_f32_e32 v45, v45
	v_pk_fma_f32 v[84:85], v[52:53], v[56:57], v[50:51]
	v_add_f32_e32 v42, 1.0, v42
	v_rcp_f32_e32 v56, v42
	v_add_f32_e32 v42, 1.0, v45
	v_lshlrev_b32_e32 v45, 16, v210
	v_mul_f32_e32 v45, 0xbfb8aa3b, v45
	v_lshlrev_b32_e32 v47, 16, v212
	v_exp_f32_e32 v45, v45
	v_mul_f32_e32 v47, 0xbfb8aa3b, v47
	v_exp_f32_e32 v47, v47
	v_rcp_f32_e32 v57, v42
	v_add_f32_e32 v42, 1.0, v45
	v_pk_fma_f32 v[86:87], v[52:53], v[58:59], v[50:51]
	v_rcp_f32_e32 v58, v42
	v_add_f32_e32 v42, 1.0, v47
	v_rcp_f32_e32 v59, v42
	s_waitcnt vmcnt(9)
	v_lshlrev_b32_e32 v42, 16, v214
	v_mul_f32_e32 v42, 0xbfb8aa3b, v42
	s_waitcnt vmcnt(7)
	v_lshlrev_b32_e32 v45, 16, v216
	v_exp_f32_e32 v42, v42
	v_mul_f32_e32 v45, 0xbfb8aa3b, v45
	v_exp_f32_e32 v45, v45
	v_pk_fma_f32 v[88:89], v[52:53], v[56:57], v[50:51]
	v_add_f32_e32 v42, 1.0, v42
	v_rcp_f32_e32 v56, v42
	v_add_f32_e32 v42, 1.0, v45
	s_waitcnt vmcnt(5)
	v_lshlrev_b32_e32 v45, 16, v218
	v_mul_f32_e32 v45, 0xbfb8aa3b, v45
	s_waitcnt vmcnt(3)
	v_lshlrev_b32_e32 v47, 16, v225
	v_exp_f32_e32 v45, v45
	v_mul_f32_e32 v47, 0xbfb8aa3b, v47
	v_exp_f32_e32 v47, v47
	v_rcp_f32_e32 v57, v42
	v_add_f32_e32 v42, 1.0, v45
	v_pk_fma_f32 v[90:91], v[52:53], v[58:59], v[50:51]
	v_rcp_f32_e32 v58, v42
	v_add_f32_e32 v42, 1.0, v47
	v_rcp_f32_e32 v59, v42
	s_waitcnt vmcnt(1)
	v_lshlrev_b32_e32 v42, 16, v227
	v_mul_f32_e32 v42, 0xbfb8aa3b, v42
	v_lshlrev_b32_e32 v45, 16, v219
	v_exp_f32_e32 v42, v42
	v_mul_f32_e32 v45, 0xbfb8aa3b, v45
	v_exp_f32_e32 v45, v45
	v_pk_mul_f32 v[82:83], v[84:85], v[84:85] op_sel:[0,1] op_sel_hi:[1,0]
	v_add_f32_e32 v42, 1.0, v42
	v_pk_fma_f32 v[92:93], v[52:53], v[56:57], v[50:51]
	v_rcp_f32_e32 v56, v42
	v_add_f32_e32 v42, 1.0, v45
	v_lshlrev_b32_e32 v45, 16, v221
	v_pk_mul_f32 v[72:73], v[82:83], v[86:87]
	v_mul_f32_e32 v45, 0xbfb8aa3b, v45
	v_lshlrev_b32_e32 v47, 16, v223
	v_pk_mul_f32 v[76:77], v[72:73], v[86:87] op_sel:[0,1] op_sel_hi:[1,0]
	v_exp_f32_e32 v45, v45
	v_mul_f32_e32 v47, 0xbfb8aa3b, v47
	v_pk_mul_f32 v[80:81], v[76:77], v[88:89]
	v_exp_f32_e32 v47, v47
	v_pk_mul_f32 v[78:79], v[80:81], v[88:89] op_sel:[0,1] op_sel_hi:[1,0]
	v_rcp_f32_e32 v57, v42
	v_pk_mul_f32 v[66:67], v[78:79], v[90:91]
	v_add_f32_e32 v42, 1.0, v45
	v_pk_mul_f32 v[74:75], v[66:67], v[90:91] op_sel:[0,1] op_sel_hi:[1,0]
	v_rcp_f32_e32 v98, v42
	v_pk_mul_f32 v[70:71], v[74:75], v[92:93]
	v_add_f32_e32 v42, 1.0, v47
	v_pk_mul_f32 v[68:69], v[70:71], v[92:93] op_sel:[0,1] op_sel_hi:[1,0]
	v_pk_fma_f32 v[94:95], v[52:53], v[58:59], v[50:51]
	v_rcp_f32_e32 v99, v42
	v_pk_mul_f32 v[58:59], v[68:69], v[94:95]
	v_pk_fma_f32 v[96:97], v[52:53], v[56:57], v[50:51]
	v_pk_mul_f32 v[60:61], v[58:59], v[94:95] op_sel:[0,1] op_sel_hi:[1,0]
	v_pk_fma_f32 v[98:99], v[52:53], v[98:99], v[50:51]
	v_pk_mul_f32 v[64:65], v[60:61], v[96:97]
	s_nop 0
	v_pk_mul_f32 v[62:63], v[64:65], v[96:97] op_sel:[0,1] op_sel_hi:[1,0]
	s_nop 0
	v_pk_mul_f32 v[56:57], v[62:63], v[98:99]
	s_nop 0
	v_mul_f32_e32 v45, v56, v99
	ds_write_b32 v135, v45
	ds_write_b128 v136, v[32:35] offset:53248
	ds_write_b128 v136, v[36:39] offset:53264
	s_waitcnt lgkmcnt(0)
	s_barrier
	ds_read2st64_b32 v[102:103], v137 offset1:2
	ds_read2st64_b32 v[100:101], v137 offset0:4 offset1:6
	s_waitcnt lgkmcnt(1)
	v_mul_f32_e32 v42, v102, v103
	s_waitcnt lgkmcnt(0)
	v_mul_f32_e32 v42, v42, v100
	v_mul_f32_e32 v42, v42, v101
	s_and_saveexec_b64 s[36:37], s[0:1]
	ds_write_b32 v143, v42
	s_or_b64 exec, exec, s[36:37]
	v_cndmask_b32_e64 v67, v102, 1.0, s[0:1]
	v_mul_f32_e32 v73, v67, v103
	v_cndmask_b32_e64 v67, v67, v73, s[2:3]
	v_mul_f32_e32 v73, v100, v67
	v_cndmask_b32_e64 v67, v67, v73, s[4:5]
	v_mul_f32_e32 v73, v101, v67
	v_cndmask_b32_e64 v100, v67, v73, s[6:7]
	v_mul_f32_e32 v67, v84, v100
	v_lshlrev_b32_e32 v47, 16, v179
	v_max_f32_e32 v67, 0xda24260, v67
	v_mul_f32_e32 v73, v82, v100
	v_rcp_f32_e32 v82, v67
	v_mul_f32_e32 v47, v67, v47
	v_lshlrev_b32_e32 v57, 16, v181
	v_max_f32_e32 v73, 0xda24260, v73
	v_cvt_pk_bf16_f32 v47, v47, s0
	v_rcp_f32_e32 v83, v73
	ds_write_b16 v144, v47
	v_mul_f32_e32 v47, v73, v57
	v_pk_add_f32 v[230:231], v[84:85], 1.0 op_sel_hi:[1,0] neg_lo:[1,0] neg_hi:[1,0]
	v_cvt_pk_bf16_f32 v47, v47, s0
	ds_write_b16 v144, v47 offset:272
	v_mul_f32_e32 v47, v230, v82
	v_cvt_pk_bf16_f32 v47, v47, s0
	ds_write_b16 v144, v47 offset:17408
	v_mul_f32_e32 v47, v231, v83
	v_cvt_pk_bf16_f32 v47, v47, s0
	ds_write_b16 v144, v47 offset:17680
	v_mul_f32_e32 v47, v72, v100
	v_lshlrev_b32_e32 v59, 16, v183
	v_max_f32_e32 v47, 0xda24260, v47
	v_mul_f32_e32 v57, v76, v100
	v_rcp_f32_e32 v72, v47
	v_mul_f32_e32 v47, v47, v59
	v_lshlrev_b32_e32 v61, 16, v203
	v_max_f32_e32 v57, 0xda24260, v57
	v_cvt_pk_bf16_f32 v47, v47, s0
	v_rcp_f32_e32 v73, v57
	ds_write_b16 v144, v47 offset:544
	v_mul_f32_e32 v47, v57, v61
; #define LAS __attribute__((address_space(3)))
; __device__ __forceinline__ unsigned pk2(float lo, float hi) { const f32x2 v = {lo, hi}; return __builtin_bit_cast(unsigned, __builtin_convertvector(v, bf16x2_t)); }
; __device__ __forceinline__ unsigned f2bf(float f) { return pk2(f, 0.f) & 0xffffu; }
; __device__ __forceinline__ float frcp(float x) { return __builtin_amdgcn_rcpf(x); }
; #define HG_ISSUE(t0n) do { _Pragma("unroll") for (int i = 0; i < 16; ++i) { const int tk = (t0n) + (dir ? 63 - (i0 + i) : (i0 + i)); const bf16_t* pr = Pb + (size_t)tk * HGP + h * 128 + dcol; \
;         rq[i] = pr[0]; rf[i] = pr[1024 * (1 + dir)]; rv[i] = pr[3072]; } } while (0)
; __device__ __forceinline__ void hgrn_chain(LAS unsigned char* lds, int cid, bf16_t* P1, const float* hg_lb, bf16_t* Ob, int ldo, int ocbase, int ocdir) {
;     ...
;           for (int i = 0; i < 16; i += 2) { const float e0 = fmaxf(pre * gc[i], 1e-30f), e1 = fmaxf(pre * gc[i + 1], 1e-30f), n0 = frcp(e0), n1 = frcp(e1), l0 = etot * n0, l1 = etot * n1;
;               QE[(i0 + i) * HLD + dcol] = (bf16_t)f2bf(gq[i] * e0); QE[(i0 + i + 1) * HLD + dcol] = (bf16_t)f2bf(gq[i + 1] * e1);
;               KE[(i0 + i) * HLD + dcol] = (bf16_t)f2bf(gk[i] * n0); KE[(i0 + i + 1) * HLD + dcol] = (bf16_t)f2bf(gk[i + 1] * n1);
;               *(LAS unsigned*)(KLT + dcol * HLS + i0 + i) = pk2(gk[i] * l0, gk[i + 1] * l1); } }
;         if (cc + 1 < 64) HG_ISSUE((dir ? 62 - cc : cc + 1) * 64);
	v_pk_add_f32 v[86:87], v[86:87], 1.0 op_sel_hi:[1,0] neg_lo:[1,0] neg_hi:[1,0]
	v_cvt_pk_bf16_f32 v47, v47, s0
	ds_write_b16 v144, v47 offset:816
	v_mul_f32_e32 v47, v86, v72
	v_cvt_pk_bf16_f32 v47, v47, s0
	ds_write_b16 v144, v47 offset:17952
	v_mul_f32_e32 v47, v87, v73
	v_cvt_pk_bf16_f32 v47, v47, s0
	v_pk_mul_f32 v[82:83], v[42:43], v[82:83] op_sel_hi:[0,1]
	ds_write_b16 v144, v47 offset:18224
	v_pk_mul_f32 v[72:73], v[42:43], v[72:73] op_sel_hi:[0,1]
	v_mul_f32_e32 v47, v80, v100
	v_lshlrev_b32_e32 v63, 16, v205
	v_pk_mul_f32 v[82:83], v[230:231], v[82:83]
	v_pk_mul_f32 v[72:73], v[86:87], v[72:73]
	v_max_f32_e32 v47, 0xda24260, v47
	v_cvt_pk_bf16_f32 v82, v82, v83
	v_cvt_pk_bf16_f32 v83, v72, v73
	v_mul_f32_e32 v57, v78, v100
	v_rcp_f32_e32 v72, v47
	v_mul_f32_e32 v47, v47, v63
	v_lshlrev_b32_e32 v65, 16, v208
	v_max_f32_e32 v57, 0xda24260, v57
	v_cvt_pk_bf16_f32 v47, v47, s0
	v_rcp_f32_e32 v73, v57
	ds_write_b16 v144, v47 offset:1088
	v_mul_f32_e32 v47, v57, v65
	v_pk_add_f32 v[88:89], v[88:89], 1.0 op_sel_hi:[1,0] neg_lo:[1,0] neg_hi:[1,0]
	v_cvt_pk_bf16_f32 v47, v47, s0
	ds_write_b16 v144, v47 offset:1360
	v_mul_f32_e32 v47, v88, v72
	v_cvt_pk_bf16_f32 v47, v47, s0
	ds_write_b16 v144, v47 offset:18496
	v_mul_f32_e32 v47, v89, v73
	v_cvt_pk_bf16_f32 v47, v47, s0
	ds_write_b16 v144, v47 offset:18768
	v_mul_f32_e32 v47, v66, v100
	v_lshlrev_b32_e32 v69, 16, v209
	v_max_f32_e32 v47, 0xda24260, v47
	v_mul_f32_e32 v57, v74, v100
	v_rcp_f32_e32 v66, v47
	v_mul_f32_e32 v47, v47, v69
	v_lshlrev_b32_e32 v71, 16, v211
	v_max_f32_e32 v57, 0xda24260, v57
	v_cvt_pk_bf16_f32 v47, v47, s0
	v_rcp_f32_e32 v67, v57
	ds_write_b16 v144, v47 offset:1632
	v_mul_f32_e32 v47, v57, v71
	v_pk_add_f32 v[90:91], v[90:91], 1.0 op_sel_hi:[1,0] neg_lo:[1,0] neg_hi:[1,0]
	v_cvt_pk_bf16_f32 v47, v47, s0
	ds_write_b16 v144, v47 offset:1904
	v_mul_f32_e32 v47, v90, v66
	v_cvt_pk_bf16_f32 v47, v47, s0
	ds_write_b16 v144, v47 offset:19040
	v_mul_f32_e32 v47, v91, v67
	v_cvt_pk_bf16_f32 v47, v47, s0
	ds_write_b16 v144, v47 offset:19312
	v_pk_mul_f32 v[66:67], v[42:43], v[66:67] op_sel_hi:[0,1]
	v_mul_f32_e32 v47, v70, v100
	v_lshlrev_b32_e32 v75, 16, v213
	v_pk_mul_f32 v[66:67], v[90:91], v[66:67]
	v_max_f32_e32 v47, 0xda24260, v47
	v_cvt_pk_bf16_f32 v85, v66, v67
	v_mul_f32_e32 v57, v68, v100
	v_rcp_f32_e32 v66, v47
	v_mul_f32_e32 v47, v47, v75
	v_lshlrev_b32_e32 v77, 16, v215
	v_max_f32_e32 v57, 0xda24260, v57
	v_cvt_pk_bf16_f32 v47, v47, s0
	v_rcp_f32_e32 v67, v57
	ds_write_b16 v144, v47 offset:2176
	v_mul_f32_e32 v47, v57, v77
	v_pk_add_f32 v[92:93], v[92:93], 1.0 op_sel_hi:[1,0] neg_lo:[1,0] neg_hi:[1,0]
	v_cvt_pk_bf16_f32 v47, v47, s0
	ds_write_b16 v144, v47 offset:2448
	v_mul_f32_e32 v47, v92, v66
	v_cvt_pk_bf16_f32 v47, v47, s0
	ds_write_b16 v144, v47 offset:19584
	v_mul_f32_e32 v47, v93, v67
	v_cvt_pk_bf16_f32 v47, v47, s0
	ds_write_b16 v144, v47 offset:19856
	v_mul_f32_e32 v47, v58, v100
	v_lshlrev_b32_e32 v79, 16, v217
	v_max_f32_e32 v47, 0xda24260, v47
	v_mul_f32_e32 v57, v60, v100
	v_rcp_f32_e32 v58, v47
	v_mul_f32_e32 v47, v47, v79
	v_lshlrev_b32_e32 v81, 16, v224
	v_max_f32_e32 v57, 0xda24260, v57
	v_cvt_pk_bf16_f32 v47, v47, s0
	v_rcp_f32_e32 v59, v57
	ds_write_b16 v144, v47 offset:2720
	v_mul_f32_e32 v47, v57, v81
	v_pk_add_f32 v[94:95], v[94:95], 1.0 op_sel_hi:[1,0] neg_lo:[1,0] neg_hi:[1,0]
	v_cvt_pk_bf16_f32 v47, v47, s0
	ds_write_b16 v144, v47 offset:2992
	v_mul_f32_e32 v47, v94, v58
	v_cvt_pk_bf16_f32 v47, v47, s0
	ds_write_b16 v144, v47 offset:20128
	v_mul_f32_e32 v47, v95, v59
	v_cvt_pk_bf16_f32 v47, v47, s0
	v_pk_mul_f32 v[66:67], v[42:43], v[66:67] op_sel_hi:[0,1]
	ds_write_b16 v144, v47 offset:20400
	v_pk_mul_f32 v[58:59], v[42:43], v[58:59] op_sel_hi:[0,1]
	v_mul_f32_e32 v47, v64, v100
	v_lshlrev_b32_e32 v229, 16, v226
	v_pk_mul_f32 v[66:67], v[92:93], v[66:67]
	v_pk_mul_f32 v[58:59], v[94:95], v[58:59]
	v_max_f32_e32 v47, 0xda24260, v47
	v_cvt_pk_bf16_f32 v66, v66, v67
	v_cvt_pk_bf16_f32 v67, v58, v59
	v_mul_f32_e32 v57, v62, v100
	v_rcp_f32_e32 v58, v47
	v_mul_f32_e32 v47, v47, v229
	s_waitcnt vmcnt(0)
	v_lshlrev_b32_e32 v232, 16, v228
	v_max_f32_e32 v57, 0xda24260, v57
	v_cvt_pk_bf16_f32 v47, v47, s0
	v_rcp_f32_e32 v59, v57
	ds_write_b16 v144, v47 offset:3264
	v_mul_f32_e32 v47, v57, v232
	v_pk_add_f32 v[96:97], v[96:97], 1.0 op_sel_hi:[1,0] neg_lo:[1,0] neg_hi:[1,0]
	v_cvt_pk_bf16_f32 v47, v47, s0
	ds_write_b16 v144, v47 offset:3536
	v_mul_f32_e32 v47, v96, v58
	v_cvt_pk_bf16_f32 v47, v47, s0
	ds_write_b16 v144, v47 offset:20672
	v_mul_f32_e32 v47, v97, v59
	v_cvt_pk_bf16_f32 v47, v47, s0
	ds_write_b16 v144, v47 offset:20944
	v_mul_f32_e32 v47, v56, v100
	v_max_f32_e32 v47, 0xda24260, v47
	v_mul_f32_e32 v45, v45, v100
	v_rcp_f32_e32 v56, v47
	v_lshlrev_b32_e32 v234, 16, v222
	v_max_f32_e32 v45, 0xda24260, v45
	v_rcp_f32_e32 v57, v45
	v_mul_f32_e32 v45, v45, v234
	v_pk_add_f32 v[98:99], v[98:99], 1.0 op_sel_hi:[1,0] neg_lo:[1,0] neg_hi:[1,0]
	v_cvt_pk_bf16_f32 v45, v45, s0
	ds_write_b16 v144, v45 offset:4080
	v_mul_f32_e32 v45, v98, v56
	v_cvt_pk_bf16_f32 v45, v45, s0
	v_lshlrev_b32_e32 v233, 16, v220
	v_pk_mul_f32 v[72:73], v[42:43], v[72:73] op_sel_hi:[0,1]
	v_pk_mul_f32 v[58:59], v[42:43], v[58:59] op_sel_hi:[0,1]
	ds_write_b16 v144, v45 offset:21216
	v_mul_f32_e32 v45, v99, v57
	v_pk_mul_f32 v[56:57], v[42:43], v[56:57] op_sel_hi:[0,1]
	v_pk_mul_f32 v[72:73], v[88:89], v[72:73]
	v_pk_mul_f32 v[58:59], v[96:97], v[58:59]
	v_mul_f32_e32 v47, v47, v233
	v_pk_mul_f32 v[56:57], v[98:99], v[56:57]
	v_cvt_pk_bf16_f32 v84, v72, v73
	v_cvt_pk_bf16_f32 v68, v58, v59
	v_cvt_pk_bf16_f32 v47, v47, s0
	v_cvt_pk_bf16_f32 v45, v45, s0
	v_cvt_pk_bf16_f32 v69, v56, v57
	s_cmp_eq_u32 s43, -1
	ds_write_b128 v136, v[82:85] offset:34816
	ds_write_b16 v144, v47 offset:3808
	ds_write_b16 v144, v45 offset:21488
	ds_write_b128 v136, v[66:69] offset:34832
	s_cbranch_scc1 .LBB0_1715
; #define HG_ISSUE(t0n) do { _Pragma("unroll") for (int i = 0; i < 16; ++i) { const int tk = (t0n) + (dir ? 63 - (i0 + i) : (i0 + i)); const bf16_t* pr = Pb + (size_t)tk * HGP + h * 128 + dcol; \
;         rq[i] = pr[0]; rf[i] = pr[1024 * (1 + dir)]; rv[i] = pr[3072]; } } while (0)
; __device__ __forceinline__ void hgrn_chain(LAS unsigned char* lds, int cid, bf16_t* P1, const float* hg_lb, bf16_t* Ob, int ldo, int ocbase, int ocdir) {
;     ...
;         if (cc + 1 < 64) HG_ISSUE((dir ? 62 - cc : cc + 1) * 64);
	s_and_b64 s[36:37], s[24:25], exec
	s_cselect_b32 s36, s42, s43
	s_lshl_b32 s36, s36, 6
	v_add_u32_e32 v32, s36, v186
	v_mad_i64_i32 v[32:33], s[44:45], v32, s40, v[48:49]
	v_add_co_u32_e32 v36, vcc, 0x1000, v32
	v_add_u32_e32 v38, s36, v187
	s_nop 0
	v_addc_co_u32_e32 v37, vcc, 0, v33, vcc
	v_mad_i64_i32 v[38:39], s[44:45], v38, s40, v[48:49]
	v_add_co_u32_e32 v58, vcc, 0x1000, v38
	v_add_u32_e32 v42, s36, v188
	v_lshl_add_u64 v[34:35], v[32:33], 0, s[30:31]
	v_addc_co_u32_e32 v59, vcc, 0, v39, vcc
	v_mad_i64_i32 v[60:61], s[44:45], v42, s40, v[48:49]
	v_lshl_add_u64 v[56:57], v[38:39], 0, s[30:31]
	v_lshl_add_u64 v[62:63], v[60:61], 0, s[30:31]
	global_load_ushort v179, v[32:33], off
	global_load_ushort v180, v[34:35], off offset:2048
	global_load_ushort v235, v[36:37], off offset:2048
	global_load_ushort v181, v[38:39], off
	global_load_ushort v182, v[56:57], off offset:2048
	global_load_ushort v236, v[58:59], off offset:2048
	global_load_ushort v183, v[60:61], off
	global_load_ushort v185, v[62:63], off offset:2048
	v_add_co_u32_e32 v32, vcc, 0x1000, v60
	v_add_u32_e32 v34, s36, v189
	s_nop 0
	v_addc_co_u32_e32 v33, vcc, 0, v61, vcc
	v_mad_i64_i32 v[34:35], s[44:45], v34, s40, v[48:49]
	v_add_co_u32_e32 v38, vcc, 0x1000, v34
	v_add_u32_e32 v47, s36, v190
	s_nop 0
	v_addc_co_u32_e32 v39, vcc, 0, v35, vcc
	v_mad_i64_i32 v[56:57], s[44:45], v47, s40, v[48:49]
	v_add_co_u32_e32 v60, vcc, 0x1000, v56
	v_add_u32_e32 v47, s36, v191
	v_lshl_add_u64 v[36:37], v[34:35], 0, s[30:31]
	v_addc_co_u32_e32 v61, vcc, 0, v57, vcc
	v_mad_i64_i32 v[62:63], s[44:45], v47, s40, v[48:49]
	v_lshl_add_u64 v[58:59], v[56:57], 0, s[30:31]
	global_load_ushort v237, v[32:33], off offset:2048
	global_load_ushort v203, v[34:35], off
	global_load_ushort v204, v[36:37], off offset:2048
	global_load_ushort v238, v[38:39], off offset:2048
	global_load_ushort v205, v[56:57], off
	global_load_ushort v206, v[58:59], off offset:2048
	global_load_ushort v239, v[60:61], off offset:2048
	global_load_ushort v208, v[62:63], off
	v_add_co_u32_e32 v34, vcc, 0x1000, v62
	v_add_u32_e32 v36, s36, v192
	s_nop 0
	v_addc_co_u32_e32 v35, vcc, 0, v63, vcc
	v_mad_i64_i32 v[36:37], s[44:45], v36, s40, v[48:49]
	v_add_co_u32_e32 v56, vcc, 0x1000, v36
	v_add_u32_e32 v58, s36, v193
	s_nop 0
	v_addc_co_u32_e32 v57, vcc, 0, v37, vcc
	v_mad_i64_i32 v[58:59], s[44:45], v58, s40, v[48:49]
	v_lshl_add_u64 v[32:33], v[62:63], 0, s[30:31]
	v_add_co_u32_e32 v62, vcc, 0x1000, v58
	v_lshl_add_u64 v[38:39], v[36:37], 0, s[30:31]
	v_lshl_add_u64 v[60:61], v[58:59], 0, s[30:31]
	v_addc_co_u32_e32 v63, vcc, 0, v59, vcc
	global_load_ushort v207, v[32:33], off offset:2048
	global_load_ushort v240, v[34:35], off offset:2048
	global_load_ushort v209, v[36:37], off
	global_load_ushort v210, v[38:39], off offset:2048
	global_load_ushort v241, v[56:57], off offset:2048
	global_load_ushort v211, v[58:59], off
	global_load_ushort v212, v[60:61], off offset:2048
	global_load_ushort v242, v[62:63], off offset:2048
	v_add_u32_e32 v32, s36, v194
	v_mad_i64_i32 v[32:33], s[44:45], v32, s40, v[48:49]
	v_add_co_u32_e32 v36, vcc, 0x1000, v32
	v_add_u32_e32 v38, s36, v195
	s_nop 0
	v_addc_co_u32_e32 v37, vcc, 0, v33, vcc
	v_mad_i64_i32 v[38:39], s[44:45], v38, s40, v[48:49]
	v_add_co_u32_e32 v58, vcc, 0x1000, v38
	v_add_u32_e32 v60, s36, v196
	v_lshl_add_u64 v[34:35], v[32:33], 0, s[30:31]
	v_addc_co_u32_e32 v59, vcc, 0, v39, vcc
	v_mad_i64_i32 v[60:61], s[44:45], v60, s40, v[48:49]
	v_lshl_add_u64 v[56:57], v[38:39], 0, s[30:31]
	v_lshl_add_u64 v[62:63], v[60:61], 0, s[30:31]
	global_load_ushort v213, v[32:33], off
	global_load_ushort v214, v[34:35], off offset:2048
	global_load_ushort v243, v[36:37], off offset:2048
	global_load_ushort v215, v[38:39], off
	global_load_ushort v216, v[56:57], off offset:2048
	global_load_ushort v244, v[58:59], off offset:2048
	global_load_ushort v217, v[60:61], off
	global_load_ushort v218, v[62:63], off offset:2048
	v_add_co_u32_e32 v32, vcc, 0x1000, v60
	v_add_u32_e32 v34, s36, v197
	s_nop 0
	v_addc_co_u32_e32 v33, vcc, 0, v61, vcc
	v_mad_i64_i32 v[34:35], s[44:45], v34, s40, v[48:49]
	v_add_co_u32_e32 v38, vcc, 0x1000, v34
	v_add_u32_e32 v56, s36, v198
	s_nop 0
	v_addc_co_u32_e32 v39, vcc, 0, v35, vcc
	v_mad_i64_i32 v[56:57], s[44:45], v56, s40, v[48:49]
	v_add_co_u32_e32 v60, vcc, 0x1000, v56
	v_add_u32_e32 v62, s36, v199
	s_nop 0
	v_addc_co_u32_e32 v61, vcc, 0, v57, vcc
	v_mad_i64_i32 v[62:63], s[44:45], v62, s40, v[48:49]
	v_add_co_u32_e32 v66, vcc, 0x1000, v62
	v_add_u32_e32 v68, s36, v201
	s_nop 0
	v_addc_co_u32_e32 v67, vcc, 0, v63, vcc
	v_mad_i64_i32 v[68:69], s[44:45], v68, s40, v[48:49]
	v_add_co_u32_e32 v72, vcc, 0x1000, v68
	v_add_u32_e32 v74, s36, v202
	s_nop 0
	v_addc_co_u32_e32 v73, vcc, 0, v69, vcc
	v_mad_i64_i32 v[74:75], s[36:37], v74, s40, v[48:49]
	v_lshl_add_u64 v[36:37], v[34:35], 0, s[30:31]
	v_lshl_add_u64 v[64:65], v[62:63], 0, s[30:31]
	v_add_co_u32_e32 v78, vcc, 0x1000, v74
	v_lshl_add_u64 v[58:59], v[56:57], 0, s[30:31]
	v_lshl_add_u64 v[70:71], v[68:69], 0, s[30:31]
	v_lshl_add_u64 v[76:77], v[74:75], 0, s[30:31]
	v_addc_co_u32_e32 v79, vcc, 0, v75, vcc
	global_load_ushort v219, v[64:65], off offset:2048
	s_nop 0
	global_load_ushort v250, v[66:67], off offset:2048
	global_load_ushort v220, v[68:69], off
	global_load_ushort v221, v[70:71], off offset:2048
	global_load_ushort v245, v[72:73], off offset:2048
	global_load_ushort v222, v[74:75], off
	global_load_ushort v223, v[76:77], off offset:2048
	global_load_ushort v246, v[78:79], off offset:2048
	global_load_ushort v247, v[32:33], off offset:2048
	global_load_ushort v224, v[34:35], off
	global_load_ushort v225, v[36:37], off offset:2048
	s_nop 0
	global_load_ushort v248, v[38:39], off offset:2048
	global_load_ushort v226, v[56:57], off
	s_nop 0
	global_load_ushort v249, v[60:61], off offset:2048
	global_load_ushort v227, v[58:59], off offset:2048
	global_load_ushort v228, v[62:63], off
	s_branch .LBB0_1715
